# DIFF attention: all 8 K-fragment LDS reads of a tile issued up front into unused VGPRs v236-251, counted lgkmcnt 7..0
# baseline (speedup 1.0000x reference)
; __device__ __forceinline__ void finishSM(f32x16& p0, f32x16& p1, float alpha, float& l_reg, bf16x8& pa0, bf16x8& pa1, bf16x8& pa2, bf16x8& pa3) {
; #pragma unroll
;   for (int r = 0; r < 16; ++r) p1[r] = __builtin_amdgcn_exp2f(p1[r]);
;   float ps = 0;
; #pragma unroll
;   for (int r = 0; r < 16; ++r) ps += p0[r];
; #pragma unroll
;   for (int r = 0; r < 16; ++r) ps += p1[r];
;   { auto rr = __builtin_amdgcn_permlane32_swap(__float_as_uint(ps), __float_as_uint(ps), false, false);
;     ps = __uint_as_float(rr[0]) + __uint_as_float(rr[1]); }
;   l_reg = l_reg * alpha + ps;
;     ...
;   PK4(p0, 0, pa0); PK4(p0, 8, pa1); PK4(p1, 0, pa2); PK4(p1, 8, pa3);
; template <int DQK, int KW, int QSP> __device__ __forceinline__ void qkt(f32x16& p0, f32x16& p1, const char* Ks, const int (&kb)[4], const bf16x8* qr, const char* qsp, const f32x16& cinit) {
;   p0 = cinit; p1 = cinit;
;   constexpr int N = DQK / 16;
;     ...
;   bf16x8 f0[2], f1[2];
;   f0[0] = KRD(0, 1); f1[0] = KRD(0, 0);
; #pragma unroll
;   for (int d0 = 0; d0 < N; ++d0) {
;     if (d0 + 1 < N) { f0[(d0 + 1) & 1] = KRD(d0 + 1, 1); f1[(d0 + 1) & 1] = KRD(d0 + 1, 0); }
;     __builtin_amdgcn_sched_barrier(0x406);
;     bf16x8 qf;
;     if constexpr (QSP > 0) { if (d0 >= N - QSP) qf = *reinterpret_cast<const bf16x8*>(qsp + (d0 - (N - QSP)) * 1024); else qf = qr[d0]; } else qf = qr[d0];
;     p0 = __builtin_amdgcn_mfma_f32_32x32x16_bf16(f0[d0 & 1], qf, p0, 0, 0, 0);
;     p1 = __builtin_amdgcn_mfma_f32_32x32x16_bf16(f1[d0 & 1], qf, p1, 0, 0, 0);
;     __builtin_amdgcn_sched_barrier(0x406); }
.LBB0_316:
	s_lshl_b32 s10, s35, 14
	s_add_i32 s8, s10, 0
	v_add_u32_e32 v102, s8, v183
	ds_read_b128 v[98:101], v102 offset:49152
	v_add_u32_e32 v103, s8, v197
	ds_read_b128 v[200:203], v102 offset:57344
	ds_read_b128 v[222:225], v103 offset:49152
	ds_read_b128 v[226:229], v103 offset:57344
	v_add_u32_e32 v252, s8, v196
	v_add_u32_e32 v253, s8, v198
	ds_read_b128 v[236:239], v252 offset:49152
	ds_read_b128 v[240:243], v252 offset:57344
	ds_read_b128 v[244:247], v253 offset:49152
	ds_read_b128 v[248:251], v253 offset:57344
	v_exp_f32_e32 v205, v85
	v_exp_f32_e32 v97, v97
	s_waitcnt lgkmcnt(7)
	v_mfma_f32_32x32x16_bf16 v[114:129], v[98:101], v[142:145], v[66:81]
	s_waitcnt lgkmcnt(6)
	v_mfma_f32_32x32x16_bf16 v[98:113], v[200:203], v[142:145], v[66:81]
	s_waitcnt lgkmcnt(5)
	v_mfma_f32_32x32x16_bf16 v[114:129], v[222:225], v[138:141], v[114:129]
	s_waitcnt lgkmcnt(4)
	v_mfma_f32_32x32x16_bf16 v[98:113], v[226:229], v[138:141], v[98:113]
	v_exp_f32_e32 v204, v84
	s_waitcnt lgkmcnt(3)
	v_mfma_f32_32x32x16_bf16 v[114:129], v[236:239], v[134:137], v[114:129]
	v_exp_f32_e32 v202, v82
	v_add_f32_e32 v82, 0, v219
	v_add_f32_e32 v82, v221, v82
	v_add_f32_e32 v82, v217, v82
	v_add_f32_e32 v82, v220, v82
	v_add_f32_e32 v82, v215, v82
	v_add_f32_e32 v82, v218, v82
	v_add_f32_e32 v82, v214, v82
	v_add_f32_e32 v82, v216, v82
	v_add_f32_e32 v82, v211, v82
	v_add_f32_e32 v82, v213, v82
	v_add_f32_e32 v82, v209, v82
	v_add_f32_e32 v82, v212, v82
	s_waitcnt lgkmcnt(2)
	v_mfma_f32_32x32x16_bf16 v[98:113], v[240:243], v[134:137], v[98:113]
	v_add_f32_e32 v82, v207, v82
	v_exp_f32_e32 v203, v83
	v_add_f32_e32 v82, v210, v82
	v_add_f32_e32 v82, v206, v82
	v_add_f32_e32 v82, v208, v82
	v_add_f32_e32 v82, v202, v82
	v_add_f32_e32 v82, v203, v82
	s_waitcnt lgkmcnt(1)
	v_mfma_f32_32x32x16_bf16 v[114:129], v[244:247], v[130:133], v[114:129]
	v_exp_f32_e32 v222, v86
	v_exp_f32_e32 v223, v87
	v_exp_f32_e32 v224, v88
	v_add_f32_e32 v82, v204, v82
	v_exp_f32_e32 v225, v89
	v_add_f32_e32 v82, v205, v82
	v_add_f32_e32 v82, v222, v82
	s_waitcnt lgkmcnt(0)
	v_mfma_f32_32x32x16_bf16 v[98:113], v[248:251], v[130:133], v[98:113]
	v_exp_f32_e32 v226, v90
	v_exp_f32_e32 v227, v91
	v_add_f32_e32 v82, v223, v82
	v_exp_f32_e32 v228, v92
	v_add_f32_e32 v82, v224, v82
	v_exp_f32_e32 v229, v93
	v_add_f32_e32 v82, v225, v82
	v_exp_f32_e32 v230, v94
	v_add_f32_e32 v82, v226, v82
	v_exp_f32_e32 v231, v95
	v_add_f32_e32 v82, v227, v82
	v_exp_f32_e32 v232, v96
	v_add_f32_e32 v82, v228, v82
	v_add_f32_e32 v82, v229, v82
	v_add_f32_e32 v82, v230, v82
	v_add_f32_e32 v82, v231, v82
	v_add_f32_e32 v82, v232, v82
	v_add_f32_e32 v200, v97, v82
	v_mov_b32_e32 v201, v200
	v_cvt_pk_bf16_f32 v82, v219, v221
	v_cvt_pk_bf16_f32 v83, v217, v220
	v_cvt_pk_bf16_f32 v84, v215, v218
	s_nop 1
	v_permlane32_swap_b32_e32 v200, v201
	v_cvt_pk_bf16_f32 v85, v214, v216
	v_permlane32_swap_b32_e32 v82, v84
	v_cvt_pk_bf16_f32 v86, v211, v213
	v_cvt_pk_bf16_f32 v87, v209, v212
	v_cvt_pk_bf16_f32 v88, v207, v210
	v_cvt_pk_bf16_f32 v89, v206, v208
	v_cvt_pk_bf16_f32 v90, v202, v203
	v_cvt_pk_bf16_f32 v91, v204, v205
	v_cvt_pk_bf16_f32 v92, v222, v223
	v_cvt_pk_bf16_f32 v93, v224, v225
	v_cvt_pk_bf16_f32 v94, v226, v227
	v_cvt_pk_bf16_f32 v95, v228, v229
	v_cvt_pk_bf16_f32 v96, v230, v231
	v_cvt_pk_bf16_f32 v97, v232, v97
	v_permlane32_swap_b32_e32 v83, v85
	v_permlane32_swap_b32_e32 v86, v88
	v_permlane32_swap_b32_e32 v87, v89
	v_permlane32_swap_b32_e32 v90, v92
	v_permlane32_swap_b32_e32 v91, v93
	v_permlane32_swap_b32_e32 v94, v96
	v_permlane32_swap_b32_e32 v95, v97
	s_lshl_b32 s13, s12, 14
	s_add_i32 s11, s13, 0
	v_add_u32_e32 v202, s11, v192
	s_waitcnt vmcnt(0)
	s_waitcnt vmcnt(3)
	ds_write_b128 v202, v[146:149]
	v_add_u32_e32 v146, s11, v193
	s_waitcnt vmcnt(1)
	ds_write_b128 v146, v[150:153]
	v_add_u32_e32 v146, s11, v194
	s_mov_b32 s8, 0xfffa0000
	s_waitcnt vmcnt(1)
	ds_write_b128 v146, v[154:157] offset:49152
	s_waitcnt vmcnt(0)
; #define SBAR() __builtin_amdgcn_sched_barrier(0)
; template <bool FIRST> __device__ __forceinline__ void partialSM_ps(f32x16& p0, f32x16& p1, float& m_reg, float& alpha, f32x16& negm) {
;   float pmax = p0[0];
; #pragma unroll
;   for (int r = 1; r < 16; ++r) pmax = fmaxf(pmax, p0[r]);
; #pragma unroll
;   for (int r = 0; r < 16; ++r) pmax = fmaxf(pmax, p1[r]);
;   { auto rr = __builtin_amdgcn_permlane32_swap(__float_as_uint(pmax), __float_as_uint(pmax), false, false);
;     pmax = fmaxf(__uint_as_float(rr[0]), __uint_as_float(rr[1])); }
;   alpha = 1.f;
;   if (FIRST || !__builtin_expect(__all(pmax <= THRL), 1)) {
; template <int D0> __device__ __forceinline__ void pv_one(f32x16& od, int vb, bf16x8 pa0, bf16x8 pa1, bf16x8 pa2, bf16x8 pa3) {
;   const s16x4 l0 = tr_read<v_rd_off(D0, 0, 0)>(vb), h0 = tr_read<v_rd_off(D0, 0, 1)>(vb), l1 = tr_read<v_rd_off(D0, 1, 0)>(vb), h1 = tr_read<v_rd_off(D0, 1, 1)>(vb);
;   const s16x4 l2 = tr_read<v_rd_off(D0, 2, 0)>(vb), h2 = tr_read<v_rd_off(D0, 2, 1)>(vb), l3 = tr_read<v_rd_off(D0, 3, 0)>(vb), h3 = tr_read<v_rd_off(D0, 3, 1)>(vb);
;   asm volatile("s_waitcnt lgkmcnt(0)" ::: "memory"); SBAR();
;     ...
;   od = __builtin_amdgcn_mfma_f32_32x32x16_bf16(pa0, PK(l0, h0), od, 0, 0, 0);
;   od = __builtin_amdgcn_mfma_f32_32x32x16_bf16(pa1, PK(l1, h1), od, 0, 0, 0);
;   od = __builtin_amdgcn_mfma_f32_32x32x16_bf16(pa2, PK(l2, h2), od, 0, 0, 0);
;   od = __builtin_amdgcn_mfma_f32_32x32x16_bf16(pa3, PK(l3, h3), od, 0, 0, 0);
;     ...
; }
; __device__ __forceinline__ void pv_d0(f32x16* o, int vb, bf16x8 pa0, bf16x8 pa1, bf16x8 pa2, bf16x8 pa3) {
;   pv_one<0>(o[0], vb, pa0, pa1, pa2, pa3); pv_one<1>(o[1], vb, pa0, pa1, pa2, pa3); pv_one<2>(o[2], vb, pa0, pa1, pa2, pa3); pv_one<3>(o[3], vb, pa0, pa1, pa2, pa3);
; }
	ds_write_b128 v146, v[158:161] offset:57344
	v_add_co_u32_e32 v146, vcc, s8, v166
	s_mov_b32 s8, 0xfffc0000
	s_nop 0
	v_addc_co_u32_e32 v147, vcc, -1, v167, vcc
	v_add_co_u32_e32 v150, vcc, s8, v166
	s_mov_b32 s8, 0xfb7a0000
	s_nop 0
	v_addc_co_u32_e32 v151, vcc, -1, v167, vcc
	v_add_co_u32_e32 v154, vcc, s8, v166
	s_mov_b32 s8, 0xfb7c0000
	s_nop 0
	v_addc_co_u32_e32 v155, vcc, -1, v167, vcc
	v_add_co_u32_e32 v158, vcc, s8, v166
	global_load_dwordx4 v[146:149], v[146:147], off
	s_nop 0
	global_load_dwordx4 v[150:153], v[150:151], off
	v_addc_co_u32_e32 v159, vcc, -1, v167, vcc
	global_load_dwordx4 v[154:157], v[154:155], off
	s_nop 0
	global_load_dwordx4 v[158:161], v[158:159], off
	v_lshl_add_u32 v218, s9, 14, v181
	ds_read_b64_tr_b16 v[202:203], v218 offset:0
	ds_read_b64_tr_b16 v[204:205], v218 offset:0x800
	ds_read_b64_tr_b16 v[206:207], v218 offset:0x1000
	ds_read_b64_tr_b16 v[208:209], v218 offset:0x1800
	ds_read_b64_tr_b16 v[210:211], v218 offset:0x2000
	ds_read_b64_tr_b16 v[212:213], v218 offset:0x2800
	ds_read_b64_tr_b16 v[214:215], v218 offset:0x3000
	ds_read_b64_tr_b16 v[216:217], v218 offset:0x3800
	s_waitcnt lgkmcnt(0)
	s_nop 0
	v_mfma_f32_32x32x16_bf16 v[2:17], v[82:85], v[202:205], v[2:17]
	ds_read_b64_tr_b16 v[202:203], v218 offset:0x200
	ds_read_b64_tr_b16 v[204:205], v218 offset:0xa00
	v_mfma_f32_32x32x16_bf16 v[2:17], v[86:89], v[206:209], v[2:17]
	ds_read_b64_tr_b16 v[206:207], v218 offset:0x1200
	ds_read_b64_tr_b16 v[208:209], v218 offset:0x1a00
	v_mfma_f32_32x32x16_bf16 v[2:17], v[90:93], v[210:213], v[2:17]
	ds_read_b64_tr_b16 v[210:211], v218 offset:0x2200
	ds_read_b64_tr_b16 v[212:213], v218 offset:0x2a00
	v_mfma_f32_32x32x16_bf16 v[2:17], v[94:97], v[214:217], v[2:17]
	ds_read_b64_tr_b16 v[214:215], v218 offset:0x3200
	ds_read_b64_tr_b16 v[216:217], v218 offset:0x3a00
	s_waitcnt lgkmcnt(0)
	v_mfma_f32_32x32x16_bf16 v[50:65], v[82:85], v[202:205], v[50:65]
	ds_read_b64_tr_b16 v[202:203], v218 offset:0x400
	ds_read_b64_tr_b16 v[204:205], v218 offset:0xc00
	v_mfma_f32_32x32x16_bf16 v[50:65], v[86:89], v[206:209], v[50:65]
	ds_read_b64_tr_b16 v[206:207], v218 offset:0x1400
	ds_read_b64_tr_b16 v[208:209], v218 offset:0x1c00
	v_mfma_f32_32x32x16_bf16 v[50:65], v[90:93], v[210:213], v[50:65]
	ds_read_b64_tr_b16 v[210:211], v218 offset:0x2400
	ds_read_b64_tr_b16 v[212:213], v218 offset:0x2c00
	v_mfma_f32_32x32x16_bf16 v[50:65], v[94:97], v[214:217], v[50:65]
	ds_read_b64_tr_b16 v[214:215], v218 offset:0x3400
	ds_read_b64_tr_b16 v[216:217], v218 offset:0x3c00
	s_waitcnt lgkmcnt(0)
	v_mfma_f32_32x32x16_bf16 v[34:49], v[82:85], v[202:205], v[34:49]
	ds_read_b64_tr_b16 v[202:203], v218 offset:0x600
	ds_read_b64_tr_b16 v[204:205], v218 offset:0xe00
	v_mfma_f32_32x32x16_bf16 v[34:49], v[86:89], v[206:209], v[34:49]
	ds_read_b64_tr_b16 v[206:207], v218 offset:0x1600
	ds_read_b64_tr_b16 v[208:209], v218 offset:0x1e00
	v_mfma_f32_32x32x16_bf16 v[34:49], v[90:93], v[210:213], v[34:49]
	ds_read_b64_tr_b16 v[210:211], v218 offset:0x2600
	ds_read_b64_tr_b16 v[212:213], v218 offset:0x2e00
	v_mfma_f32_32x32x16_bf16 v[34:49], v[94:97], v[214:217], v[34:49]
	ds_read_b64_tr_b16 v[214:215], v218 offset:0x3600
	ds_read_b64_tr_b16 v[216:217], v218 offset:0x3e00
	s_waitcnt lgkmcnt(0)
	v_mfma_f32_32x32x16_bf16 v[18:33], v[82:85], v[202:205], v[18:33]
	v_max_f32_e32 v82, v115, v115
	v_max_f32_e32 v83, v114, v114
	v_max_f32_e32 v82, v83, v82
	v_max3_f32 v82, v82, v116, v117
	v_max3_f32 v82, v82, v118, v119
	v_max3_f32 v82, v82, v120, v121
	v_max3_f32 v82, v82, v122, v123
	v_mfma_f32_32x32x16_bf16 v[18:33], v[86:89], v[206:209], v[18:33]
	v_max3_f32 v82, v82, v124, v125
	v_max3_f32 v82, v82, v126, v127
	v_max3_f32 v82, v82, v128, v129
	v_max3_f32 v82, v82, v98, v99
	v_max3_f32 v82, v82, v100, v101
	v_max3_f32 v82, v82, v102, v103
	v_max3_f32 v82, v82, v104, v105
	v_mfma_f32_32x32x16_bf16 v[18:33], v[90:93], v[210:213], v[18:33]
	v_max3_f32 v82, v82, v106, v107
	v_max3_f32 v82, v82, v108, v109
	v_max3_f32 v82, v82, v110, v111
	v_max3_f32 v82, v82, v112, v113
	v_mov_b32_e32 v83, v82
	s_nop 1
	v_permlane32_swap_b32_e32 v82, v83
	v_mfma_f32_32x32x16_bf16 v[18:33], v[94:97], v[214:217], v[18:33]
	v_max_f32_e32 v83, v83, v83
	v_max_f32_e32 v82, v82, v82
	v_max_f32_e32 v82, v82, v83
	v_cmp_ge_f32_e32 vcc, s0, v82
	s_cmp_eq_u64 vcc, exec
	s_cbranch_scc0 .LBB0_331
	v_mov_b32_e32 v203, 1.0

; template <bool FIRST> __device__ __forceinline__ void partialSM_ps(f32x16& p0, f32x16& p1, float& m_reg, float& alpha, f32x16& negm) {
;     ...
; #pragma unroll
;   for (int r = 0; r < 16; ++r) p0[r] = __builtin_amdgcn_exp2f(p0[r]);
; __device__ __forceinline__ void finishSM(f32x16& p0, f32x16& p1, float alpha, float& l_reg, bf16x8& pa0, bf16x8& pa1, bf16x8& pa2, bf16x8& pa3) {
; #pragma unroll
;   for (int r = 0; r < 16; ++r) p1[r] = __builtin_amdgcn_exp2f(p1[r]);
;   float ps = 0;
; #pragma unroll
;   for (int r = 0; r < 16; ++r) ps += p0[r];
; #pragma unroll
;   for (int r = 0; r < 16; ++r) ps += p1[r];
;   { auto rr = __builtin_amdgcn_permlane32_swap(__float_as_uint(ps), __float_as_uint(ps), false, false);
;     ps = __uint_as_float(rr[0]) + __uint_as_float(rr[1]); }
;   l_reg = l_reg * alpha + ps;
;     ...
;   PK4(p0, 0, pa0); PK4(p0, 8, pa1); PK4(p1, 0, pa2); PK4(p1, 8, pa3);
; template <int DQK, int KW, int QSP> __device__ __forceinline__ void qkt(f32x16& p0, f32x16& p1, const char* Ks, const int (&kb)[4], const bf16x8* qr, const char* qsp, const f32x16& cinit) {
;   p0 = cinit; p1 = cinit;
;   constexpr int N = DQK / 16;
;     ...
;   bf16x8 f0[2], f1[2];
;   f0[0] = KRD(0, 1); f1[0] = KRD(0, 0);
; #pragma unroll
;   for (int d0 = 0; d0 < N; ++d0) {
;     if (d0 + 1 < N) { f0[(d0 + 1) & 1] = KRD(d0 + 1, 1); f1[(d0 + 1) & 1] = KRD(d0 + 1, 0); }
;     __builtin_amdgcn_sched_barrier(0x406);
;     bf16x8 qf;
;     if constexpr (QSP > 0) { if (d0 >= N - QSP) qf = *reinterpret_cast<const bf16x8*>(qsp + (d0 - (N - QSP)) * 1024); else qf = qr[d0]; } else qf = qr[d0];
;     p0 = __builtin_amdgcn_mfma_f32_32x32x16_bf16(f0[d0 & 1], qf, p0, 0, 0, 0);
;     p1 = __builtin_amdgcn_mfma_f32_32x32x16_bf16(f1[d0 & 1], qf, p1, 0, 0, 0);
;     __builtin_amdgcn_sched_barrier(0x406); }
.LBB0_322:
	s_add_i32 s8, s12, 1
	s_cmp_lg_u32 s12, 2
	s_cselect_b32 s35, s8, 0
	v_exp_f32_e32 v202, v114
	v_exp_f32_e32 v220, v115
	v_exp_f32_e32 v221, v116
	v_exp_f32_e32 v222, v117
	v_exp_f32_e32 v223, v118
	v_exp_f32_e32 v224, v119
	v_exp_f32_e32 v225, v120
	v_exp_f32_e32 v226, v121
	v_exp_f32_e32 v227, v122
	v_exp_f32_e32 v228, v123
	v_exp_f32_e32 v229, v124
	v_exp_f32_e32 v230, v125
	v_exp_f32_e32 v231, v126
	v_exp_f32_e32 v232, v127
	v_exp_f32_e32 v233, v128
	v_exp_f32_e32 v234, v129
	v_add_u32_e32 v86, s11, v183
	ds_read_b128 v[82:85], v86 offset:49152
	v_add_u32_e32 v87, s11, v197
	ds_read_b128 v[204:207], v86 offset:57344
	ds_read_b128 v[208:211], v87 offset:49152
	ds_read_b128 v[212:215], v87 offset:57344
	v_add_u32_e32 v252, s11, v196
	v_add_u32_e32 v253, s11, v198
	ds_read_b128 v[236:239], v252 offset:49152
	ds_read_b128 v[240:243], v252 offset:57344
	ds_read_b128 v[244:247], v253 offset:49152
	ds_read_b128 v[248:251], v253 offset:57344
	v_exp_f32_e32 v235, v112
	v_exp_f32_e32 v113, v113
	s_waitcnt lgkmcnt(7)
	v_mfma_f32_32x32x16_bf16 v[114:129], v[82:85], v[142:145], v[66:81]
	s_waitcnt lgkmcnt(6)
	v_mfma_f32_32x32x16_bf16 v[82:97], v[204:207], v[142:145], v[66:81]
	s_waitcnt lgkmcnt(5)
	v_mfma_f32_32x32x16_bf16 v[114:129], v[208:211], v[138:141], v[114:129]
	s_waitcnt lgkmcnt(4)
	v_mfma_f32_32x32x16_bf16 v[82:97], v[212:215], v[138:141], v[82:97]
	s_waitcnt lgkmcnt(3)
	v_mfma_f32_32x32x16_bf16 v[114:129], v[236:239], v[134:137], v[114:129]
	v_exp_f32_e32 v206, v98
	v_add_f32_e32 v98, 0, v202
	v_add_f32_e32 v98, v220, v98
	v_add_f32_e32 v98, v221, v98
	v_add_f32_e32 v98, v222, v98
	v_add_f32_e32 v98, v223, v98
	v_add_f32_e32 v98, v224, v98
	v_add_f32_e32 v98, v225, v98
	v_add_f32_e32 v98, v226, v98
	v_add_f32_e32 v98, v227, v98
	v_add_f32_e32 v98, v228, v98
	s_waitcnt lgkmcnt(2)
	v_mfma_f32_32x32x16_bf16 v[82:97], v[240:243], v[134:137], v[82:97]
	v_add_f32_e32 v98, v229, v98
	v_add_f32_e32 v98, v230, v98
	v_add_f32_e32 v98, v231, v98
	v_exp_f32_e32 v207, v99
	v_add_f32_e32 v98, v232, v98
	v_add_f32_e32 v98, v233, v98
	v_add_f32_e32 v98, v234, v98
	s_waitcnt lgkmcnt(1)
	v_mfma_f32_32x32x16_bf16 v[114:129], v[244:247], v[130:133], v[114:129]
	v_exp_f32_e32 v208, v100
	v_exp_f32_e32 v209, v101
	v_exp_f32_e32 v210, v102
	v_add_f32_e32 v98, v206, v98
	v_exp_f32_e32 v211, v103
	v_add_f32_e32 v98, v207, v98
	v_add_f32_e32 v98, v208, v98
	s_waitcnt lgkmcnt(0)
	v_mfma_f32_32x32x16_bf16 v[82:97], v[248:251], v[130:133], v[82:97]
	v_exp_f32_e32 v212, v104
	v_exp_f32_e32 v213, v105
	v_add_f32_e32 v98, v209, v98
	v_exp_f32_e32 v214, v106
	v_add_f32_e32 v98, v210, v98
	v_exp_f32_e32 v215, v107
	v_add_f32_e32 v98, v211, v98
	v_exp_f32_e32 v216, v108
	v_add_f32_e32 v98, v212, v98
	v_exp_f32_e32 v217, v109
	v_add_f32_e32 v98, v213, v98
	v_exp_f32_e32 v218, v110
	v_add_f32_e32 v98, v214, v98
	v_exp_f32_e32 v219, v111
	v_add_f32_e32 v98, v215, v98
	v_add_f32_e32 v98, v216, v98
	v_add_f32_e32 v98, v217, v98
	v_add_f32_e32 v98, v218, v98
	v_add_f32_e32 v98, v219, v98
	v_add_f32_e32 v98, v235, v98
	v_add_f32_e32 v204, v113, v98
	v_mov_b32_e32 v205, v204
	v_cvt_pk_bf16_f32 v98, v202, v220
	v_cvt_pk_bf16_f32 v99, v221, v222
	v_cvt_pk_bf16_f32 v100, v223, v224
	v_cvt_pk_bf16_f32 v101, v225, v226
	v_cvt_pk_bf16_f32 v102, v227, v228
	v_cvt_pk_bf16_f32 v103, v229, v230
	v_cvt_pk_bf16_f32 v104, v231, v232
	v_cvt_pk_bf16_f32 v105, v233, v234
	v_cvt_pk_bf16_f32 v106, v206, v207
	v_cvt_pk_bf16_f32 v107, v208, v209
	v_cvt_pk_bf16_f32 v108, v210, v211
	v_cvt_pk_bf16_f32 v109, v212, v213
	v_cvt_pk_bf16_f32 v110, v214, v215
	v_cvt_pk_bf16_f32 v111, v216, v217
	v_cvt_pk_bf16_f32 v112, v218, v219
	v_cvt_pk_bf16_f32 v113, v235, v113
	s_nop 1
	v_permlane32_swap_b32_e32 v204, v205
	v_permlane32_swap_b32_e32 v98, v100
	v_permlane32_swap_b32_e32 v99, v101
	v_permlane32_swap_b32_e32 v102, v104
	v_permlane32_swap_b32_e32 v103, v105
	v_permlane32_swap_b32_e32 v106, v108
	v_permlane32_swap_b32_e32 v107, v109
	v_permlane32_swap_b32_e32 v110, v112
	v_permlane32_swap_b32_e32 v111, v113
	s_lshl_b32 s33, s35, 14
	s_add_i32 s36, s33, 0
	s_waitcnt vmcnt(0)
	v_add_u32_e32 v202, s36, v192
	s_cmp_ge_u32 s30, s31
	s_waitcnt vmcnt(3)
	ds_write_b128 v202, v[146:149]
	v_add_u32_e32 v202, s36, v193
	s_cselect_b64 s[8:9], -1, 0
	s_waitcnt vmcnt(2)
	ds_write_b128 v202, v[150:153]
	v_add_u32_e32 v202, s33, v195
	s_and_b64 vcc, exec, s[8:9]
	s_waitcnt vmcnt(1)
	ds_write_b128 v202, v[154:157] offset:49152
	s_waitcnt vmcnt(0)
	ds_write_b128 v202, v[158:161] offset:57344
	s_cbranch_vccnz .LBB0_324
	v_add_co_u32_e32 v146, vcc, 0xfffe0000, v166
	s_nop 1
	v_addc_co_u32_e32 v147, vcc, -1, v167, vcc
	v_add_co_u32_e32 v150, vcc, 0xfb7e0000, v166
	s_nop 1
	v_addc_co_u32_e32 v151, vcc, -1, v167, vcc
	v_add_co_u32_e32 v158, vcc, 0xfb800000, v166
	global_load_dwordx4 v[146:149], v[146:147], off
	s_nop 0
	global_load_dwordx4 v[154:157], v[150:151], off
	v_addc_co_u32_e32 v159, vcc, -1, v167, vcc
	global_load_dwordx4 v[150:153], v[166:167], off
	s_nop 0
	global_load_dwordx4 v[158:161], v[158:159], off
